# input-projection GEMM phase: co-resident block start stagger removed as well
# baseline (speedup 1.0000x reference)
.LBB0_277:
	s_or_b64 exec, exec, s[0:1]
	s_and_b32 s0, s33, 1
	s_bitcmp1_b32 s33, 0
	s_cselect_b64 s[2:3], -1, 0
	v_writelane_b32 v246, s2, 26
	s_cmp_eq_u32 s0, 0
	s_waitcnt lgkmcnt(0)
	s_barrier
	v_writelane_b32 v246, s3, 27
	s_cbranch_scc1 .LBB0_279
	s_nop 0
